# MLA: extended fast loop + 4-tile masked tail with per-wave variants replacing the compiler general loop
# speedup vs baseline: 1.0056x; 1.0056x over previous
.Lmf_tail:
	s_mov_b32 s18, s83
	s_mov_b32 s17, 2
	v_lshlrev_b32_e32 v241, 2, v219
	v_sub_u32_e32 v240, v198, v241
	s_add_i32 s19, s73, 31
	s_lshl_b32 s84, s18, 6
	v_subrev_u32_e32 v241, s84, v240
	v_cmp_gt_i32_e64 vcc, 0, v241
	v_cmp_gt_i32_e64 s[42:43], 1, v241
	v_cmp_gt_i32_e64 s[44:45], 2, v241
	v_cmp_gt_i32_e64 s[46:47], 3, v241
	v_cmp_gt_i32_e64 s[48:49], 8, v241
	v_cmp_gt_i32_e64 s[50:51], 9, v241
	v_cndmask_b32_e64 v66, v66, v213, vcc
	v_cndmask_b32_e64 v67, v67, v213, s[42:43]
	v_cndmask_b32_e64 v68, v68, v213, s[44:45]
	v_cndmask_b32_e64 v69, v69, v213, s[46:47]
	v_cndmask_b32_e64 v70, v70, v213, s[48:49]
	v_cndmask_b32_e64 v71, v71, v213, s[50:51]
	v_cmp_gt_i32_e64 vcc, 10, v241
	v_cmp_gt_i32_e64 s[42:43], 11, v241
	v_cmp_gt_i32_e64 s[44:45], 16, v241
	v_cmp_gt_i32_e64 s[46:47], 17, v241
	v_cmp_gt_i32_e64 s[48:49], 18, v241
	v_cmp_gt_i32_e64 s[50:51], 19, v241
	v_cndmask_b32_e64 v72, v72, v213, vcc
	v_cndmask_b32_e64 v73, v73, v213, s[42:43]
	v_cndmask_b32_e64 v74, v74, v213, s[44:45]
	v_cndmask_b32_e64 v75, v75, v213, s[46:47]
	v_cndmask_b32_e64 v76, v76, v213, s[48:49]
	v_cndmask_b32_e64 v77, v77, v213, s[50:51]
	v_cmp_gt_i32_e64 vcc, 24, v241
	v_cmp_gt_i32_e64 s[42:43], 25, v241
	v_cmp_gt_i32_e64 s[44:45], 26, v241
	v_cmp_gt_i32_e64 s[46:47], 27, v241
	v_cmp_gt_i32_e64 s[48:49], 32, v241
	v_cmp_gt_i32_e64 s[50:51], 33, v241
	v_cndmask_b32_e64 v78, v78, v213, vcc
	v_cndmask_b32_e64 v79, v79, v213, s[42:43]
	v_cndmask_b32_e64 v80, v80, v213, s[44:45]
	v_cndmask_b32_e64 v81, v81, v213, s[46:47]
	v_cndmask_b32_e64 v82, v82, v213, s[48:49]
	v_cndmask_b32_e64 v83, v83, v213, s[50:51]
	v_cmp_gt_i32_e64 vcc, 34, v241
	v_cmp_gt_i32_e64 s[42:43], 35, v241
	v_cmp_gt_i32_e64 s[44:45], 40, v241
	v_cmp_gt_i32_e64 s[46:47], 41, v241
	v_cmp_gt_i32_e64 s[48:49], 42, v241
	v_cmp_gt_i32_e64 s[50:51], 43, v241
	v_cndmask_b32_e64 v84, v84, v213, vcc
	v_cndmask_b32_e64 v85, v85, v213, s[42:43]
	v_cndmask_b32_e64 v86, v86, v213, s[44:45]
	v_cndmask_b32_e64 v87, v87, v213, s[46:47]
	v_cndmask_b32_e64 v88, v88, v213, s[48:49]
	v_cndmask_b32_e64 v89, v89, v213, s[50:51]
	v_cmp_gt_i32_e64 vcc, 48, v241
	v_cmp_gt_i32_e64 s[42:43], 49, v241
	v_cmp_gt_i32_e64 s[44:45], 50, v241
	v_cmp_gt_i32_e64 s[46:47], 51, v241
	v_cmp_gt_i32_e64 s[48:49], 56, v241
	v_cmp_gt_i32_e64 s[50:51], 57, v241
	v_cndmask_b32_e64 v90, v90, v213, vcc
	v_cndmask_b32_e64 v91, v91, v213, s[42:43]
	v_cndmask_b32_e64 v92, v92, v213, s[44:45]
	v_cndmask_b32_e64 v93, v93, v213, s[46:47]
	v_cndmask_b32_e64 v94, v94, v213, s[48:49]
	v_cndmask_b32_e64 v95, v95, v213, s[50:51]
	v_cmp_gt_i32_e64 vcc, 58, v241
	v_cmp_gt_i32_e64 s[42:43], 59, v241
	s_nop 1
	v_cndmask_b32_e64 v96, v96, v213, vcc
	v_cndmask_b32_e64 v97, v97, v213, s[42:43]
